# n128 K-loops: tail dummy stage loads re-read the current K-tile (L2-hot) instead of K-tile 0
# speedup vs baseline: 1.0078x; 1.0078x over previous
.LBB0_216:
	s_waitcnt vmcnt(6)
	s_add_i32 s42, s29, 3
	s_waitcnt lgkmcnt(0)
	s_barrier
	s_cmp_lt_u32 s29, 13
	s_cselect_b32 s94, s42, s29
	s_mul_i32 s42, s47, 0xc000
	v_or_b32_e32 v196, s42, v245
	ds_read_b128 v[184:187], v196 offset:0
	ds_read_b128 v[188:191], v196 offset:1024
	ds_read_b128 v[192:195], v196 offset:2048
	ds_read_b128 v[196:199], v196 offset:3072
	s_setprio 1
	v_mfma_f32_16x16x32_bf16 v[108:111], v[80:83], v[120:123], v[108:111]
	s_lshl_b64 s[62:63], s[94:95], 7
	v_mfma_f32_16x16x32_bf16 v[104:107], v[112:115], v[120:123], v[104:107]
	v_mfma_f32_16x16x32_bf16 v[100:103], v[80:83], v[128:131], v[100:103]
	v_mfma_f32_16x16x32_bf16 v[96:99], v[112:115], v[128:131], v[96:99]
	v_mfma_f32_16x16x32_bf16 v[108:111], v[88:91], v[124:127], v[108:111]
	v_mfma_f32_16x16x32_bf16 v[104:107], v[116:119], v[124:127], v[104:107]
	v_mfma_f32_16x16x32_bf16 v[100:103], v[88:91], v[132:135], v[100:103]
	v_mfma_f32_16x16x32_bf16 v[96:99], v[116:119], v[132:135], v[96:99]
	s_setprio 0
	s_add_u32 s64, s40, s62
	s_mul_i32 s43, s45, 0xc000
	s_addc_u32 s65, s41, s63
	s_add_i32 s43, s58, s43
	v_lshl_add_u64 v[120:121], s[64:65], 0, v[212:213]
	s_mov_b32 m0, s43
	v_add_u32_e32 v200, s42, v230
	global_load_lds_dwordx4 v[120:121], off
	v_lshl_add_u64 v[120:121], s[64:65], 0, v[216:217]
	s_add_i32 m0, s43, 0x2000
	s_nop 0
	global_load_lds_dwordx4 v[120:121], off
	ds_read_b128 v[120:123], v200 offset:0
	ds_read_b128 v[124:127], v200 offset:1024
	ds_read_b128 v[128:131], v200 offset:2048
	ds_read_b128 v[132:135], v200 offset:3072
	s_setprio 1
	v_mfma_f32_16x16x32_bf16 v[92:95], v[80:83], v[136:139], v[92:95]
	v_mfma_f32_16x16x32_bf16 v[84:87], v[112:115], v[136:139], v[84:87]
	v_mfma_f32_16x16x32_bf16 v[76:79], v[80:83], v[144:147], v[76:79]
	v_mfma_f32_16x16x32_bf16 v[72:75], v[112:115], v[144:147], v[72:75]
	v_mfma_f32_16x16x32_bf16 v[92:95], v[88:91], v[140:143], v[92:95]
	v_mfma_f32_16x16x32_bf16 v[84:87], v[116:119], v[140:143], v[84:87]
	v_mfma_f32_16x16x32_bf16 v[76:79], v[88:91], v[148:151], v[76:79]
	v_mfma_f32_16x16x32_bf16 v[72:75], v[116:119], v[148:151], v[72:75]
	s_setprio 0
	s_add_u32 s64, s48, s62
	s_addc_u32 s65, s49, s63
	s_add_i32 m0, s43, 0x4000
	v_lshl_add_u64 v[136:137], s[64:65], 0, v[210:211]
	global_load_lds_dwordx4 v[136:137], off
	v_lshl_add_u64 v[136:137], s[64:65], 0, v[214:215]
	s_add_i32 m0, s43, 0x6000
	v_add_u32_e32 v148, 0x1000, v200
	global_load_lds_dwordx4 v[136:137], off
	ds_read_b128 v[136:139], v148 offset:0
	ds_read_b128 v[140:143], v148 offset:1024
	ds_read_b128 v[144:147], v148 offset:2048
	ds_read_b128 v[148:151], v148 offset:3072
	s_setprio 1
	v_mfma_f32_16x16x32_bf16 v[68:71], v[80:83], v[152:155], v[68:71]
	v_mfma_f32_16x16x32_bf16 v[64:67], v[112:115], v[152:155], v[64:67]
	v_mfma_f32_16x16x32_bf16 v[60:63], v[80:83], v[164:167], v[60:63]
	v_mfma_f32_16x16x32_bf16 v[56:59], v[112:115], v[164:167], v[56:59]
	v_mfma_f32_16x16x32_bf16 v[68:71], v[88:91], v[160:163], v[68:71]
	v_mfma_f32_16x16x32_bf16 v[64:67], v[116:119], v[160:163], v[64:67]
	v_mfma_f32_16x16x32_bf16 v[60:63], v[88:91], v[176:179], v[60:63]
	v_mfma_f32_16x16x32_bf16 v[56:59], v[116:119], v[176:179], v[56:59]
	s_setprio 0
	s_add_u32 s62, s50, s62
	s_addc_u32 s63, s51, s63
	s_add_i32 m0, s43, 0x8000
	v_lshl_add_u64 v[152:153], s[62:63], 0, v[210:211]
	global_load_lds_dwordx4 v[152:153], off
	v_lshl_add_u64 v[152:153], s[62:63], 0, v[214:215]
	s_add_i32 m0, s43, 0xa000
	v_add_u32_e32 v200, s42, v231
	global_load_lds_dwordx4 v[152:153], off
	ds_read_b128 v[152:155], v200 offset:0
	ds_read_b128 v[160:163], v200 offset:1024
	ds_read_b128 v[164:167], v200 offset:2048
	ds_read_b128 v[176:179], v200 offset:3072
	s_setprio 1
	v_mfma_f32_16x16x32_bf16 v[52:55], v[80:83], v[156:159], v[52:55]
	v_mfma_f32_16x16x32_bf16 v[48:51], v[112:115], v[156:159], v[48:51]
	v_mfma_f32_16x16x32_bf16 v[8:11], v[80:83], v[172:175], v[8:11]
	v_mfma_f32_16x16x32_bf16 v[20:23], v[112:115], v[172:175], v[20:23]
	v_mfma_f32_16x16x32_bf16 v[52:55], v[88:91], v[168:171], v[52:55]
	v_mfma_f32_16x16x32_bf16 v[48:51], v[116:119], v[168:171], v[48:51]
	v_mfma_f32_16x16x32_bf16 v[8:11], v[88:91], v[180:183], v[8:11]
	v_mfma_f32_16x16x32_bf16 v[20:23], v[116:119], v[180:183], v[20:23]
	s_setprio 0
	s_add_i32 s43, s47, 1
	s_cmp_lg_u32 s47, 2
	v_add_u32_e32 v80, 0x1000, v200
	ds_read_b128 v[156:159], v80 offset:0
	ds_read_b128 v[168:171], v80 offset:1024
	ds_read_b128 v[172:175], v80 offset:2048
	ds_read_b128 v[180:183], v80 offset:3072
	s_cselect_b32 s45, s43, 0
	s_waitcnt vmcnt(6)
	s_add_i32 s43, s29, 4
	s_waitcnt lgkmcnt(0)
	s_barrier
	s_cmp_lt_u32 s29, 12
	s_cselect_b32 s94, s43, s29
	s_mul_i32 s43, s45, 0xc000
	v_or_b32_e32 v116, s43, v245
	ds_read_b128 v[80:83], v116 offset:0
	ds_read_b128 v[88:91], v116 offset:1024
	ds_read_b128 v[112:115], v116 offset:2048
	ds_read_b128 v[116:119], v116 offset:3072
	s_setprio 1
	v_mfma_f32_16x16x32_bf16 v[108:111], v[184:187], v[120:123], v[108:111]
	s_lshl_b64 s[62:63], s[94:95], 7
	v_mfma_f32_16x16x32_bf16 v[104:107], v[192:195], v[120:123], v[104:107]
	v_mfma_f32_16x16x32_bf16 v[100:103], v[184:187], v[128:131], v[100:103]
	v_mfma_f32_16x16x32_bf16 v[96:99], v[192:195], v[128:131], v[96:99]
	v_mfma_f32_16x16x32_bf16 v[108:111], v[188:191], v[124:127], v[108:111]
	v_mfma_f32_16x16x32_bf16 v[104:107], v[196:199], v[124:127], v[104:107]
	v_mfma_f32_16x16x32_bf16 v[100:103], v[188:191], v[132:135], v[100:103]
	v_mfma_f32_16x16x32_bf16 v[96:99], v[196:199], v[132:135], v[96:99]
	s_setprio 0
	s_add_u32 s64, s40, s62
	s_addc_u32 s65, s41, s63
	s_add_i32 s42, s58, s42
	v_lshl_add_u64 v[120:121], s[64:65], 0, v[212:213]
	s_mov_b32 m0, s42
	v_add_u32_e32 v200, s43, v230
	global_load_lds_dwordx4 v[120:121], off
	v_lshl_add_u64 v[120:121], s[64:65], 0, v[216:217]
	s_add_i32 m0, s42, 0x2000
	s_nop 0
	global_load_lds_dwordx4 v[120:121], off
	ds_read_b128 v[120:123], v200 offset:0
	ds_read_b128 v[124:127], v200 offset:1024
	ds_read_b128 v[128:131], v200 offset:2048
	ds_read_b128 v[132:135], v200 offset:3072
	s_setprio 1
	v_mfma_f32_16x16x32_bf16 v[92:95], v[184:187], v[136:139], v[92:95]
	v_mfma_f32_16x16x32_bf16 v[84:87], v[192:195], v[136:139], v[84:87]
	v_mfma_f32_16x16x32_bf16 v[76:79], v[184:187], v[144:147], v[76:79]
	v_mfma_f32_16x16x32_bf16 v[72:75], v[192:195], v[144:147], v[72:75]
	v_mfma_f32_16x16x32_bf16 v[92:95], v[188:191], v[140:143], v[92:95]
	v_mfma_f32_16x16x32_bf16 v[84:87], v[196:199], v[140:143], v[84:87]
	v_mfma_f32_16x16x32_bf16 v[76:79], v[188:191], v[148:151], v[76:79]
	v_mfma_f32_16x16x32_bf16 v[72:75], v[196:199], v[148:151], v[72:75]
	s_setprio 0
	s_add_u32 s64, s48, s62
	s_addc_u32 s65, s49, s63
	s_add_i32 m0, s42, 0x4000
	v_lshl_add_u64 v[136:137], s[64:65], 0, v[210:211]
	global_load_lds_dwordx4 v[136:137], off
	v_lshl_add_u64 v[136:137], s[64:65], 0, v[214:215]
	s_add_i32 m0, s42, 0x6000
	v_add_u32_e32 v148, 0x1000, v200
	global_load_lds_dwordx4 v[136:137], off
	ds_read_b128 v[136:139], v148 offset:0
	ds_read_b128 v[140:143], v148 offset:1024
	ds_read_b128 v[144:147], v148 offset:2048
	ds_read_b128 v[148:151], v148 offset:3072
	s_setprio 1
	v_mfma_f32_16x16x32_bf16 v[68:71], v[184:187], v[152:155], v[68:71]
	v_mfma_f32_16x16x32_bf16 v[64:67], v[192:195], v[152:155], v[64:67]
	v_mfma_f32_16x16x32_bf16 v[60:63], v[184:187], v[164:167], v[60:63]
	v_mfma_f32_16x16x32_bf16 v[56:59], v[192:195], v[164:167], v[56:59]
	v_mfma_f32_16x16x32_bf16 v[68:71], v[188:191], v[160:163], v[68:71]
	v_mfma_f32_16x16x32_bf16 v[64:67], v[196:199], v[160:163], v[64:67]
	v_mfma_f32_16x16x32_bf16 v[60:63], v[188:191], v[176:179], v[60:63]
	v_mfma_f32_16x16x32_bf16 v[56:59], v[196:199], v[176:179], v[56:59]
	s_setprio 0
	s_add_u32 s62, s50, s62
	s_addc_u32 s63, s51, s63
	s_add_i32 m0, s42, 0x8000
	v_lshl_add_u64 v[152:153], s[62:63], 0, v[210:211]
	global_load_lds_dwordx4 v[152:153], off
	v_lshl_add_u64 v[152:153], s[62:63], 0, v[214:215]
	s_add_i32 m0, s42, 0xa000
	v_add_u32_e32 v200, s43, v231
	global_load_lds_dwordx4 v[152:153], off
	ds_read_b128 v[152:155], v200 offset:0
	ds_read_b128 v[160:163], v200 offset:1024
	ds_read_b128 v[164:167], v200 offset:2048
	ds_read_b128 v[176:179], v200 offset:3072
	s_setprio 1
	v_mfma_f32_16x16x32_bf16 v[52:55], v[184:187], v[156:159], v[52:55]
	v_mfma_f32_16x16x32_bf16 v[48:51], v[192:195], v[156:159], v[48:51]
	v_mfma_f32_16x16x32_bf16 v[8:11], v[184:187], v[172:175], v[8:11]
	v_mfma_f32_16x16x32_bf16 v[20:23], v[192:195], v[172:175], v[20:23]
	v_mfma_f32_16x16x32_bf16 v[52:55], v[188:191], v[168:171], v[52:55]
	v_mfma_f32_16x16x32_bf16 v[48:51], v[196:199], v[168:171], v[48:51]
	v_mfma_f32_16x16x32_bf16 v[8:11], v[188:191], v[180:183], v[8:11]
	v_mfma_f32_16x16x32_bf16 v[20:23], v[196:199], v[180:183], v[20:23]
	s_setprio 0
	s_add_i32 s42, s45, 1
	s_cmp_lg_u32 s45, 2
	s_cselect_b32 s47, s42, 0
	s_add_i32 s42, s29, 2
	v_add_u32_e32 v180, 0x1000, v200
	s_cmp_gt_u32 s29, 13
	s_mov_b32 s29, s42
	ds_read_b128 v[156:159], v180 offset:0
	ds_read_b128 v[168:171], v180 offset:1024
	ds_read_b128 v[172:175], v180 offset:2048
	ds_read_b128 v[180:183], v180 offset:3072
	s_cbranch_scc0 .LBB0_216
	s_and_b32 s28, s28, 0xfffffc00
	s_addk_i32 s28, 0xf400
	s_and_b64 s[0:1], s[0:1], exec
	s_cselect_b32 s0, 0, s28
	s_ashr_i32 s1, s0, 31
	s_lshl_b64 s[0:1], s[0:1], 2
	s_add_u32 s0, s55, s0
	s_addc_u32 s1, s56, s1
	v_lshl_add_u64 v[112:113], v[218:219], 2, s[0:1]
	v_readlane_b32 s0, v254, 52
	s_waitcnt vmcnt(0) lgkmcnt(0)
	s_barrier
	v_readlane_b32 s1, v254, 53
	v_mov_b32_e32 v80, 0
	s_andn2_b64 vcc, exec, s[0:1]
	v_cndmask_b32_e64 v81, 0, 1, s[0:1]
	v_cmp_ne_u32_e64 s[40:41], 1, v81
	v_mov_b32_e32 v88, 0
	v_mov_b32_e32 v89, v80
	v_mov_b32_e32 v90, 0
	v_mov_b32_e32 v91, 0
	s_cbranch_vccnz .LBB0_219
	global_load_dwordx4 v[88:91], v[112:113], off

.LBB0_607:
	s_waitcnt vmcnt(6)
	s_nop 0
	s_waitcnt lgkmcnt(0)
	s_barrier
	s_add_i32 s59, s29, 3
	s_mul_i32 s64, s58, 0xc000
	s_cmp_lt_u32 s29, 41
	v_or_b32_e32 v196, s64, v231
	s_cselect_b32 s94, s59, s29
	ds_read_b128 v[184:187], v196 offset:0
	ds_read_b128 v[188:191], v196 offset:1024
	ds_read_b128 v[192:195], v196 offset:2048
	ds_read_b128 v[196:199], v196 offset:3072
	s_setprio 1
	v_mfma_f32_16x16x32_bf16 v[108:111], v[80:83], v[120:123], v[108:111]
	s_lshl_b64 s[60:61], s[94:95], 7
	v_mfma_f32_16x16x32_bf16 v[104:107], v[112:115], v[120:123], v[104:107]
	v_mfma_f32_16x16x32_bf16 v[100:103], v[80:83], v[128:131], v[100:103]
	v_mfma_f32_16x16x32_bf16 v[96:99], v[112:115], v[128:131], v[96:99]
	v_mfma_f32_16x16x32_bf16 v[108:111], v[88:91], v[124:127], v[108:111]
	v_mfma_f32_16x16x32_bf16 v[104:107], v[116:119], v[124:127], v[104:107]
	v_mfma_f32_16x16x32_bf16 v[100:103], v[88:91], v[132:135], v[100:103]
	v_mfma_f32_16x16x32_bf16 v[96:99], v[116:119], v[132:135], v[96:99]
	s_setprio 0
	s_add_u32 s62, s40, s60
	s_mul_i32 s57, s57, 0xc000
	s_addc_u32 s63, s41, s61
	s_add_i32 s57, s53, s57
	v_lshl_add_u64 v[120:121], s[62:63], 0, v[212:213]
	s_mov_b32 m0, s57
	v_add_u32_e32 v200, s64, v245
	global_load_lds_dwordx4 v[120:121], off
	v_lshl_add_u64 v[120:121], s[62:63], 0, v[216:217]
	s_add_i32 m0, s57, 0x2000
	s_nop 0
	global_load_lds_dwordx4 v[120:121], off
	ds_read_b128 v[120:123], v200 offset:0
	ds_read_b128 v[124:127], v200 offset:1024
	ds_read_b128 v[128:131], v200 offset:2048
	ds_read_b128 v[132:135], v200 offset:3072
	s_setprio 1
	v_mfma_f32_16x16x32_bf16 v[92:95], v[80:83], v[136:139], v[92:95]
	v_mfma_f32_16x16x32_bf16 v[84:87], v[112:115], v[136:139], v[84:87]
	v_mfma_f32_16x16x32_bf16 v[76:79], v[80:83], v[144:147], v[76:79]
	v_mfma_f32_16x16x32_bf16 v[72:75], v[112:115], v[144:147], v[72:75]
	v_mfma_f32_16x16x32_bf16 v[92:95], v[88:91], v[140:143], v[92:95]
	v_mfma_f32_16x16x32_bf16 v[84:87], v[116:119], v[140:143], v[84:87]
	v_mfma_f32_16x16x32_bf16 v[76:79], v[88:91], v[148:151], v[76:79]
	v_mfma_f32_16x16x32_bf16 v[72:75], v[116:119], v[148:151], v[72:75]
	s_setprio 0
	s_add_u32 s62, s42, s60
	s_addc_u32 s63, s43, s61
	s_add_i32 m0, s57, 0x4000
	v_lshl_add_u64 v[136:137], s[62:63], 0, v[210:211]
	global_load_lds_dwordx4 v[136:137], off
	v_lshl_add_u64 v[136:137], s[62:63], 0, v[214:215]
	s_add_i32 m0, s57, 0x6000
	v_add_u32_e32 v148, 0x1000, v200
	global_load_lds_dwordx4 v[136:137], off
	ds_read_b128 v[136:139], v148 offset:0
	ds_read_b128 v[140:143], v148 offset:1024
	ds_read_b128 v[144:147], v148 offset:2048
	ds_read_b128 v[148:151], v148 offset:3072
	s_setprio 1
	v_mfma_f32_16x16x32_bf16 v[68:71], v[80:83], v[152:155], v[68:71]
	v_mfma_f32_16x16x32_bf16 v[64:67], v[112:115], v[152:155], v[64:67]
	v_mfma_f32_16x16x32_bf16 v[60:63], v[80:83], v[164:167], v[60:63]
	v_mfma_f32_16x16x32_bf16 v[56:59], v[112:115], v[164:167], v[56:59]
	v_mfma_f32_16x16x32_bf16 v[68:71], v[88:91], v[160:163], v[68:71]
	v_mfma_f32_16x16x32_bf16 v[64:67], v[116:119], v[160:163], v[64:67]
	v_mfma_f32_16x16x32_bf16 v[60:63], v[88:91], v[176:179], v[60:63]
	v_mfma_f32_16x16x32_bf16 v[56:59], v[116:119], v[176:179], v[56:59]
	s_setprio 0
	s_add_u32 s60, s44, s60
	s_addc_u32 s61, s45, s61
	s_add_i32 m0, s57, 0x8000
	v_lshl_add_u64 v[152:153], s[60:61], 0, v[210:211]
	global_load_lds_dwordx4 v[152:153], off
	v_lshl_add_u64 v[152:153], s[60:61], 0, v[214:215]
	s_add_i32 m0, s57, 0xa000
	v_add_u32_e32 v200, s64, v248
	global_load_lds_dwordx4 v[152:153], off
	ds_read_b128 v[152:155], v200 offset:0
	ds_read_b128 v[160:163], v200 offset:1024
	ds_read_b128 v[164:167], v200 offset:2048
	ds_read_b128 v[176:179], v200 offset:3072
	s_setprio 1
	v_mfma_f32_16x16x32_bf16 v[52:55], v[80:83], v[156:159], v[52:55]
	v_mfma_f32_16x16x32_bf16 v[48:51], v[112:115], v[156:159], v[48:51]
	v_mfma_f32_16x16x32_bf16 v[8:11], v[80:83], v[172:175], v[8:11]
	v_mfma_f32_16x16x32_bf16 v[16:19], v[112:115], v[172:175], v[16:19]
	v_mfma_f32_16x16x32_bf16 v[52:55], v[88:91], v[168:171], v[52:55]
	v_mfma_f32_16x16x32_bf16 v[48:51], v[116:119], v[168:171], v[48:51]
	v_mfma_f32_16x16x32_bf16 v[8:11], v[88:91], v[180:183], v[8:11]
	v_mfma_f32_16x16x32_bf16 v[16:19], v[116:119], v[180:183], v[16:19]
	s_setprio 0
	s_add_i32 s57, s58, 1
	v_add_u32_e32 v80, 0x1000, v200
	ds_read_b128 v[156:159], v80 offset:0
	ds_read_b128 v[168:171], v80 offset:1024
	ds_read_b128 v[172:175], v80 offset:2048
	ds_read_b128 v[180:183], v80 offset:3072
	s_cmp_lg_u32 s58, 2
	s_waitcnt vmcnt(6)
	s_cselect_b32 s57, s57, 0
	s_waitcnt lgkmcnt(0)
	s_barrier
	s_add_i32 s58, s29, 4
	s_mul_i32 s62, s57, 0xc000
	s_cmp_lt_u32 s29, 40
	v_or_b32_e32 v116, s62, v231
	s_cselect_b32 s94, s58, s29
	ds_read_b128 v[80:83], v116 offset:0
	ds_read_b128 v[88:91], v116 offset:1024
	ds_read_b128 v[112:115], v116 offset:2048
	ds_read_b128 v[116:119], v116 offset:3072
	s_setprio 1
	v_mfma_f32_16x16x32_bf16 v[108:111], v[184:187], v[120:123], v[108:111]
	s_lshl_b64 s[58:59], s[94:95], 7
	v_mfma_f32_16x16x32_bf16 v[104:107], v[192:195], v[120:123], v[104:107]
	v_mfma_f32_16x16x32_bf16 v[100:103], v[184:187], v[128:131], v[100:103]
	v_mfma_f32_16x16x32_bf16 v[96:99], v[192:195], v[128:131], v[96:99]
	v_mfma_f32_16x16x32_bf16 v[108:111], v[188:191], v[124:127], v[108:111]
	v_mfma_f32_16x16x32_bf16 v[104:107], v[196:199], v[124:127], v[104:107]
	v_mfma_f32_16x16x32_bf16 v[100:103], v[188:191], v[132:135], v[100:103]
	v_mfma_f32_16x16x32_bf16 v[96:99], v[196:199], v[132:135], v[96:99]
	s_setprio 0
	s_add_u32 s60, s40, s58
	s_addc_u32 s61, s41, s59
	s_add_i32 s63, s53, s64
	v_lshl_add_u64 v[120:121], s[60:61], 0, v[212:213]
	s_mov_b32 m0, s63
	v_add_u32_e32 v200, s62, v245
	global_load_lds_dwordx4 v[120:121], off
	v_lshl_add_u64 v[120:121], s[60:61], 0, v[216:217]
	s_add_i32 m0, s63, 0x2000
	s_nop 0
	global_load_lds_dwordx4 v[120:121], off
	ds_read_b128 v[120:123], v200 offset:0
	ds_read_b128 v[124:127], v200 offset:1024
	ds_read_b128 v[128:131], v200 offset:2048
	ds_read_b128 v[132:135], v200 offset:3072
	s_setprio 1
	v_mfma_f32_16x16x32_bf16 v[92:95], v[184:187], v[136:139], v[92:95]
	v_mfma_f32_16x16x32_bf16 v[84:87], v[192:195], v[136:139], v[84:87]
	v_mfma_f32_16x16x32_bf16 v[76:79], v[184:187], v[144:147], v[76:79]
	v_mfma_f32_16x16x32_bf16 v[72:75], v[192:195], v[144:147], v[72:75]
	v_mfma_f32_16x16x32_bf16 v[92:95], v[188:191], v[140:143], v[92:95]
	v_mfma_f32_16x16x32_bf16 v[84:87], v[196:199], v[140:143], v[84:87]
	v_mfma_f32_16x16x32_bf16 v[76:79], v[188:191], v[148:151], v[76:79]
	v_mfma_f32_16x16x32_bf16 v[72:75], v[196:199], v[148:151], v[72:75]
	s_setprio 0
	s_add_u32 s60, s42, s58
	s_addc_u32 s61, s43, s59
	s_add_i32 m0, s63, 0x4000
	v_lshl_add_u64 v[136:137], s[60:61], 0, v[210:211]
	global_load_lds_dwordx4 v[136:137], off
	v_lshl_add_u64 v[136:137], s[60:61], 0, v[214:215]
	s_add_i32 m0, s63, 0x6000
	v_add_u32_e32 v148, 0x1000, v200
	global_load_lds_dwordx4 v[136:137], off
	ds_read_b128 v[136:139], v148 offset:0
	ds_read_b128 v[140:143], v148 offset:1024
	ds_read_b128 v[144:147], v148 offset:2048
	ds_read_b128 v[148:151], v148 offset:3072
	s_setprio 1
	v_mfma_f32_16x16x32_bf16 v[68:71], v[184:187], v[152:155], v[68:71]
	v_mfma_f32_16x16x32_bf16 v[64:67], v[192:195], v[152:155], v[64:67]
	v_mfma_f32_16x16x32_bf16 v[60:63], v[184:187], v[164:167], v[60:63]
	v_mfma_f32_16x16x32_bf16 v[56:59], v[192:195], v[164:167], v[56:59]
	v_mfma_f32_16x16x32_bf16 v[68:71], v[188:191], v[160:163], v[68:71]
	v_mfma_f32_16x16x32_bf16 v[64:67], v[196:199], v[160:163], v[64:67]
	v_mfma_f32_16x16x32_bf16 v[60:63], v[188:191], v[176:179], v[60:63]
	v_mfma_f32_16x16x32_bf16 v[56:59], v[196:199], v[176:179], v[56:59]
	s_setprio 0
	s_add_u32 s58, s44, s58
	s_addc_u32 s59, s45, s59
	s_add_i32 m0, s63, 0x8000
	v_lshl_add_u64 v[152:153], s[58:59], 0, v[210:211]
	global_load_lds_dwordx4 v[152:153], off
	v_lshl_add_u64 v[152:153], s[58:59], 0, v[214:215]
	s_add_i32 m0, s63, 0xa000
	v_add_u32_e32 v200, s62, v248
	global_load_lds_dwordx4 v[152:153], off
	ds_read_b128 v[152:155], v200 offset:0
	ds_read_b128 v[160:163], v200 offset:1024
	ds_read_b128 v[164:167], v200 offset:2048
	ds_read_b128 v[176:179], v200 offset:3072
	s_setprio 1
	v_mfma_f32_16x16x32_bf16 v[52:55], v[184:187], v[156:159], v[52:55]
	v_mfma_f32_16x16x32_bf16 v[48:51], v[192:195], v[156:159], v[48:51]
	v_mfma_f32_16x16x32_bf16 v[8:11], v[184:187], v[172:175], v[8:11]
	v_mfma_f32_16x16x32_bf16 v[16:19], v[192:195], v[172:175], v[16:19]
	v_mfma_f32_16x16x32_bf16 v[52:55], v[188:191], v[168:171], v[52:55]
	v_mfma_f32_16x16x32_bf16 v[48:51], v[196:199], v[168:171], v[48:51]
	v_mfma_f32_16x16x32_bf16 v[8:11], v[188:191], v[180:183], v[8:11]
	v_mfma_f32_16x16x32_bf16 v[16:19], v[196:199], v[180:183], v[16:19]
	s_setprio 0
	s_add_i32 s58, s57, 1
	s_cmp_lg_u32 s57, 2
	s_cselect_b32 s58, s58, 0
	s_add_i32 s59, s29, 2
	v_add_u32_e32 v180, 0x1000, v200
	s_cmp_gt_u32 s29, 41
	s_mov_b32 s29, s59
	ds_read_b128 v[156:159], v180 offset:0
	ds_read_b128 v[168:171], v180 offset:1024
	ds_read_b128 v[172:175], v180 offset:2048
	ds_read_b128 v[180:183], v180 offset:3072
	s_cbranch_scc0 .LBB0_607
	s_and_b32 s28, s28, 0xfffffc00
	s_addk_i32 s28, 0xf400
	s_and_b64 s[0:1], s[0:1], exec
	s_cselect_b32 s0, 0, s28
	s_ashr_i32 s1, s0, 31
	s_lshl_b64 s[0:1], s[0:1], 2
	s_waitcnt vmcnt(0) lgkmcnt(0)
	s_barrier
	s_add_u32 s0, s51, s0
	s_addc_u32 s1, s50, s1
	v_mov_b32_e32 v80, 0
	v_cndmask_b32_e64 v81, 0, 1, s[2:3]
	v_lshl_add_u64 v[112:113], v[218:219], 2, s[0:1]
	v_cmp_ne_u32_e64 s[40:41], 1, v81
	s_andn2_b64 vcc, exec, s[2:3]
	v_mov_b32_e32 v88, 0
	v_mov_b32_e32 v89, v80
	v_mov_b32_e32 v90, 0
	v_mov_b32_e32 v91, 0
	s_cbranch_vccnz .LBB0_610
	global_load_dwordx4 v[88:91], v[112:113], off
